# epilogue-loads-issued-before-the-align-epilogue-barrier-kinds-2-3-4
# baseline (speedup 1.0000x reference)
.LBB0_313:
	v_mov_b32_e32 v56, 0
	v_mov_b32_e32 v57, v56
	v_mov_b32_e32 v58, v56
	v_mov_b32_e32 v59, v56
	v_mov_b64_e32 v[62:63], v[58:59]
	v_mov_b64_e32 v[44:45], v[56:57]
	v_mov_b64_e32 v[40:41], v[56:57]
	v_mov_b64_e32 v[28:29], v[56:57]
	v_mov_b64_e32 v[24:25], v[56:57]
	v_mov_b64_e32 v[12:13], v[56:57]
	v_mov_b64_e32 v[8:9], v[56:57]
	v_mov_b64_e32 v[52:53], v[56:57]
	v_mov_b64_e32 v[48:49], v[56:57]
	v_mov_b64_e32 v[36:37], v[56:57]
	v_mov_b64_e32 v[32:33], v[56:57]
	v_mov_b64_e32 v[20:21], v[56:57]
	v_mov_b64_e32 v[16:17], v[56:57]
	v_mov_b64_e32 v[4:5], v[56:57]
	s_waitcnt lgkmcnt(0)
	v_mov_b64_e32 v[0:1], v[56:57]
	v_mov_b32_e32 v129, v56
	v_mov_b32_e32 v128, v56
	v_mov_b32_e32 v127, v56
	v_mov_b32_e32 v126, v56
	v_mov_b32_e32 v125, v56
	v_mov_b32_e32 v124, v56
	v_mov_b32_e32 v123, v56
	v_mov_b32_e32 v122, v56
	v_mov_b32_e32 v113, v56
	v_mov_b32_e32 v112, v56
	v_mov_b32_e32 v111, v56
	v_mov_b32_e32 v110, v56
	v_mov_b32_e32 v109, v56
	v_mov_b32_e32 v108, v56
	v_mov_b32_e32 v107, v56
	v_mov_b32_e32 v106, v56
	v_mov_b32_e32 v95, v56
	v_mov_b32_e32 v94, v56
	v_mov_b32_e32 v93, v56
	v_mov_b32_e32 v92, v56
	v_mov_b32_e32 v91, v56
	v_mov_b32_e32 v90, v56
	v_mov_b32_e32 v89, v56
	v_mov_b32_e32 v88, v56
	v_mov_b32_e32 v79, v56
	v_mov_b32_e32 v78, v56
	v_mov_b32_e32 v77, v56
	v_mov_b32_e32 v76, v56
	v_mov_b32_e32 v75, v56
	v_mov_b32_e32 v74, v56
	v_mov_b32_e32 v73, v56
	v_mov_b32_e32 v72, v56
	v_mov_b32_e32 v121, v56
	v_mov_b32_e32 v120, v56
	v_mov_b32_e32 v119, v56
	v_mov_b32_e32 v118, v56
	v_mov_b32_e32 v117, v56
	v_mov_b32_e32 v116, v56
	v_mov_b32_e32 v115, v56
	v_mov_b32_e32 v114, v56
	v_mov_b32_e32 v105, v56
	v_mov_b32_e32 v104, v56
	v_mov_b32_e32 v103, v56
	v_mov_b32_e32 v102, v56
	v_mov_b32_e32 v101, v56
	v_mov_b32_e32 v100, v56
	v_mov_b32_e32 v99, v56
	v_mov_b32_e32 v98, v56
	v_mov_b32_e32 v87, v56
	v_mov_b32_e32 v86, v56
	v_mov_b32_e32 v85, v56
	v_mov_b32_e32 v84, v56
	v_mov_b32_e32 v83, v56
	v_mov_b32_e32 v82, v56
	v_mov_b32_e32 v81, v56
	v_mov_b32_e32 v80, v56
	v_mov_b32_e32 v71, v56
	v_mov_b32_e32 v70, v56
	v_mov_b32_e32 v69, v56
	v_mov_b32_e32 v68, v56
	v_mov_b32_e32 v67, v56
	v_mov_b32_e32 v66, v56
	v_mov_b32_e32 v65, v56
	v_mov_b32_e32 v64, v56
	v_mov_b64_e32 v[60:61], v[56:57]
	v_mov_b64_e32 v[46:47], v[58:59]
	v_mov_b64_e32 v[42:43], v[58:59]
	v_mov_b64_e32 v[30:31], v[58:59]
	v_mov_b64_e32 v[26:27], v[58:59]
	v_mov_b64_e32 v[14:15], v[58:59]
	v_mov_b64_e32 v[10:11], v[58:59]
	v_mov_b64_e32 v[54:55], v[58:59]
	v_mov_b64_e32 v[50:51], v[58:59]
	v_mov_b64_e32 v[38:39], v[58:59]
	v_mov_b64_e32 v[34:35], v[58:59]
	v_mov_b64_e32 v[22:23], v[58:59]
	v_mov_b64_e32 v[18:19], v[58:59]
	v_mov_b64_e32 v[6:7], v[58:59]
	v_mov_b64_e32 v[2:3], v[58:59]
	s_branch .Lres_pre

.Lres_pre:
	v_lshl_or_b32 v158, s68, 8, v221
	v_lshl_add_u32 v160, s87, 8, v220
	v_ashrrev_i32_e32 v159, 31, v158
	s_waitcnt lgkmcnt(0)
	v_lshlrev_b64 v[182:183], 1, v[158:159]
	v_ashrrev_i32_e32 v161, 31, v160
	v_lshl_add_u64 v[162:163], s[22:23], 0, v[182:183]
	v_lshlrev_b64 v[184:185], 11, v[160:161]
	v_lshl_add_u64 v[130:131], v[162:163], 0, v[184:185]
	global_load_dwordx4 v[178:181], v[130:131], off
	global_load_dwordx4 v[154:157], v[130:131], off offset:256
	v_or_b32_e32 v172, 16, v160
	v_ashrrev_i32_e32 v173, 31, v172
	v_or_b32_e32 v168, 32, v160
	v_lshlrev_b64 v[174:175], 11, v[172:173]
	v_ashrrev_i32_e32 v169, 31, v168
	v_or_b32_e32 v164, 48, v160
	v_lshl_add_u64 v[130:131], v[162:163], 0, v[174:175]
	v_lshlrev_b64 v[170:171], 11, v[168:169]
	v_ashrrev_i32_e32 v165, 31, v164
	global_load_dwordx4 v[150:153], v[130:131], off
	global_load_dwordx4 v[146:149], v[130:131], off offset:256
	v_lshl_add_u64 v[130:131], v[162:163], 0, v[170:171]
	v_lshlrev_b64 v[166:167], 11, v[164:165]
	global_load_dwordx4 v[142:145], v[130:131], off
	global_load_dwordx4 v[138:141], v[130:131], off offset:256
	v_lshl_add_u64 v[130:131], v[162:163], 0, v[166:167]
	global_load_dwordx4 v[134:137], v[130:131], off
	s_nop 0
	global_load_dwordx4 v[130:133], v[130:131], off offset:256
	s_and_b64 vcc, exec, s[70:71]
	s_cbranch_vccz .LBB0_316

.LBB0_316:
	v_lshl_add_u64 v[184:185], s[22:23], 0, v[184:185]
	v_lshl_add_u64 v[182:183], v[184:185], 0, v[182:183]
	v_cmp_lt_i32_e32 vcc, v233, v228
	s_lshl_b32 s30, s68, 2
	s_ashr_i32 s31, s30, 31
	v_cndmask_b32_e32 v96, v227, v233, vcc
	v_lshlrev_b32_e32 v176, 2, v96
	v_cmp_lt_i32_e32 vcc, v234, v228
	s_waitcnt vmcnt(0)
	v_lshlrev_b32_e32 v186, 16, v178
	v_and_b32_e32 v187, 0xffff0000, v178
	v_lshlrev_b32_e32 v178, 16, v179
	v_and_b32_e32 v179, 0xffff0000, v179
	v_lshlrev_b32_e32 v188, 16, v180
	v_and_b32_e32 v189, 0xffff0000, v180
	v_lshlrev_b32_e32 v180, 16, v181
	v_and_b32_e32 v181, 0xffff0000, v181
	v_pk_add_f32 v[128:129], v[128:129], v[178:179]
	v_pk_add_f32 v[126:127], v[126:127], v[186:187]
	v_pk_add_f32 v[178:179], v[124:125], v[180:181]
	v_pk_add_f32 v[180:181], v[122:123], v[188:189]
	v_cvt_pk_bf16_f32 v122, v126, v127
	v_cvt_pk_bf16_f32 v123, v128, v129
	v_cvt_pk_bf16_f32 v124, v180, v181
	v_cvt_pk_bf16_f32 v125, v178, v179
	global_store_dwordx4 v[182:183], v[122:125], off
	v_cndmask_b32_e32 v96, v227, v234, vcc
	v_lshlrev_b32_e32 v96, 2, v96
	v_mul_f32_e32 v122, v127, v127
	v_mul_f32_e32 v123, v129, v129
	v_fmac_f32_e32 v122, v126, v126
	v_fmac_f32_e32 v123, v128, v128
	v_add_f32_e32 v122, v122, v123
	v_mul_f32_e32 v123, v181, v181
	v_fmac_f32_e32 v123, v180, v180
	v_add_f32_e32 v122, v123, v122
	v_mul_f32_e32 v123, v179, v179
	v_fmac_f32_e32 v123, v178, v178
	v_add_f32_e32 v177, v123, v122
	v_lshlrev_b32_e32 v122, 16, v154
	v_and_b32_e32 v123, 0xffff0000, v154
	v_lshlrev_b32_e32 v124, 16, v155
	v_and_b32_e32 v125, 0xffff0000, v155
	v_lshlrev_b32_e32 v126, 16, v156
	v_and_b32_e32 v127, 0xffff0000, v156
	v_lshlrev_b32_e32 v128, 16, v157
	v_and_b32_e32 v129, 0xffff0000, v157
	v_pk_add_f32 v[120:121], v[120:121], v[124:125]
	v_pk_add_f32 v[118:119], v[118:119], v[122:123]
	v_pk_add_f32 v[122:123], v[116:117], v[128:129]
	v_pk_add_f32 v[124:125], v[114:115], v[126:127]
	v_cvt_pk_bf16_f32 v114, v118, v119
	v_cvt_pk_bf16_f32 v115, v120, v121
	v_cvt_pk_bf16_f32 v116, v124, v125
	v_cvt_pk_bf16_f32 v117, v122, v123
	global_store_dwordx4 v[182:183], v[114:117], off offset:256
	s_nop 1
	v_mul_f32_e32 v114, v119, v119
	v_mul_f32_e32 v115, v121, v121
	v_fmac_f32_e32 v114, v118, v118
	v_fmac_f32_e32 v115, v120, v120
	v_add_f32_e32 v114, v114, v115
	v_mul_f32_e32 v115, v125, v125
	v_fmac_f32_e32 v115, v124, v124
	v_add_f32_e32 v114, v115, v114
	v_mul_f32_e32 v115, v123, v123
	v_fmac_f32_e32 v115, v122, v122
	v_add_f32_e32 v114, v115, v114
	v_add_f32_e32 v114, v177, v114
	ds_bpermute_b32 v115, v176, v114
	s_waitcnt lgkmcnt(0)
	v_add_f32_e32 v114, v114, v115
	ds_bpermute_b32 v115, v96, v114
	s_and_saveexec_b64 s[40:41], s[36:37]
	s_cbranch_execz .LBB0_318
	v_readlane_b32 s42, v252, 26
	v_lshlrev_b64 v[116:117], 6, v[160:161]
	v_readlane_b32 s43, v252, 27
	s_lshl_b32 s68, s13, 2
	s_waitcnt lgkmcnt(0)
	v_add_f32_e32 v114, v114, v115
	v_lshl_add_u64 v[116:117], s[42:43], 0, v[116:117]
	v_lshl_add_u64 v[116:117], s[30:31], 2, v[116:117]
	v_lshl_add_u64 v[116:117], v[116:117], 0, s[68:69]
	global_store_dword v[116:117], v114, off

.LBB0_378:
	s_lshl_b32 s5, s5, 8
	s_lshl_b32 s6, s6, 7
	s_add_i32 s5, s5, s6
	v_add_u32_e32 v130, s5, v222
	v_ashrrev_i32_e32 v131, 31, v130
	v_lshlrev_b64 v[132:133], 6, v[130:131]
	v_lshl_add_u64 v[132:133], v[204:205], 0, v[132:133]
	global_load_dwordx4 v[136:139], v[132:133], off
	global_load_dwordx4 v[140:143], v[132:133], off offset:1024
	global_load_dwordx4 v[144:147], v[132:133], off offset:2048
	global_load_dwordx4 v[148:151], v[132:133], off offset:3072
	v_add_u32_e32 v168, 0x80, v130
	v_ashrrev_i32_e32 v169, 31, v168
	v_lshlrev_b64 v[168:169], 6, v[168:169]
	v_lshl_add_u64 v[168:169], v[204:205], 0, v[168:169]
	global_load_dwordx4 v[152:155], v[168:169], off
	global_load_dwordx4 v[156:159], v[168:169], off offset:1024
	global_load_dwordx4 v[160:163], v[168:169], off offset:2048
	global_load_dwordx4 v[164:167], v[168:169], off offset:3072
	s_and_b64 vcc, exec, s[66:67]
	s_cbranch_vccz .LBB0_380
	s_barrier
.LBB0_380:
	s_lshl_b32 s4, s4, 7
	s_ashr_i32 s5, s4, 31
	s_lshl_b64 s[38:39], s[4:5], 1
	s_waitcnt vmcnt(7)
	v_add_f32_e32 v131, v136, v137
	v_add_f32_e32 v132, v138, v139
	v_add_f32_e32 v131, v131, v132
	v_mov_b32_e32 v132, v131
	s_nop 1
	v_permlane16_swap_b32_e32 v131, v132
	v_add_f32_e32 v131, v131, v132
	v_mov_b32_e32 v132, v131
	s_nop 1
	v_permlane32_swap_b32_e32 v131, v132
	v_add_f32_e32 v131, v131, v132
	v_fmamk_f32 v131, v131, 0x3a800000, v225
	v_cmp_gt_f32_e32 vcc, s3, v131
	v_mul_f32_e32 v132, 0x4b800000, v131
	s_nop 0
	v_cndmask_b32_e32 v131, v131, v132, vcc
	v_rsq_f32_e32 v131, v131
	s_nop 0
	v_mul_f32_e32 v132, 0x45800000, v131
	v_cndmask_b32_e32 v132, v131, v132, vcc
	v_pk_mul_f32 v[126:127], v[126:127], v[132:133] op_sel_hi:[1,0]
	v_pk_mul_f32 v[122:123], v[122:123], v[132:133] op_sel_hi:[1,0]
	v_mul_f32_e32 v131, 0xbfb8aa3b, v126
	v_exp_f32_e32 v131, v131
	v_pk_mul_f32 v[124:125], v[124:125], v[132:133] op_sel_hi:[1,0]
	v_pk_mul_f32 v[118:119], v[118:119], v[132:133] op_sel_hi:[1,0]
	v_pk_mul_f32 v[114:115], v[114:115], v[132:133] op_sel_hi:[1,0]
	v_add_f32_e32 v131, 1.0, v131
	v_rcp_f32_e32 v134, v131
	v_mul_f32_e32 v131, 0xbfb8aa3b, v127
	v_exp_f32_e32 v131, v131
	v_pk_mul_f32 v[116:117], v[116:117], v[132:133] op_sel_hi:[1,0]
	v_add_f32_e32 v131, 1.0, v131
	v_rcp_f32_e32 v135, v131
	s_nop 0
	v_pk_mul_f32 v[126:127], v[126:127], v[134:135]
	s_nop 0
	v_pk_mul_f32 v[122:123], v[122:123], v[126:127]
	v_pk_mul_f32 v[126:127], v[128:129], v[132:133] op_sel_hi:[1,0]
	s_nop 0
	v_mul_f32_e32 v128, 0xbfb8aa3b, v126
	v_mul_f32_e32 v129, 0xbfb8aa3b, v127
	v_exp_f32_e32 v128, v128
	v_exp_f32_e32 v129, v129
	v_add_f32_e32 v128, 1.0, v128
	v_add_f32_e32 v129, 1.0, v129
	v_rcp_f32_e32 v128, v128
	v_rcp_f32_e32 v129, v129
	s_nop 0
	v_pk_mul_f32 v[126:127], v[126:127], v[128:129]
	s_nop 0
	v_pk_mul_f32 v[124:125], v[124:125], v[126:127]
	v_mul_f32_e32 v126, 0xbfb8aa3b, v118
	v_mul_f32_e32 v127, 0xbfb8aa3b, v119
	v_exp_f32_e32 v126, v126
	v_exp_f32_e32 v127, v127
	v_add_f32_e32 v126, 1.0, v126
	v_add_f32_e32 v127, 1.0, v127
	v_rcp_f32_e32 v126, v126
	v_rcp_f32_e32 v127, v127
	s_nop 0
	v_pk_mul_f32 v[118:119], v[118:119], v[126:127]
	s_nop 0
	v_pk_mul_f32 v[118:119], v[114:115], v[118:119]
	v_pk_mul_f32 v[114:115], v[120:121], v[132:133] op_sel_hi:[1,0]
	s_nop 0
	v_mul_f32_e32 v120, 0xbfb8aa3b, v114
	v_mul_f32_e32 v121, 0xbfb8aa3b, v115
	v_exp_f32_e32 v120, v120
	v_exp_f32_e32 v121, v121
	v_add_f32_e32 v120, 1.0, v120
	v_add_f32_e32 v121, 1.0, v121
	v_rcp_f32_e32 v120, v120
	v_rcp_f32_e32 v121, v121
	s_nop 0
	v_pk_mul_f32 v[114:115], v[114:115], v[120:121]
	s_nop 0
	v_pk_mul_f32 v[120:121], v[116:117], v[114:115]
	v_cvt_pk_bf16_f32 v116, v118, v119
	v_mov_b64_e32 v[118:119], s[62:63]
	v_cvt_pk_bf16_f32 v117, v120, v121
	v_mad_i64_i32 v[120:121], s[6:7], v130, s16, v[118:119]
	v_lshl_add_u64 v[120:121], v[120:121], 0, s[38:39]
	v_lshl_add_u64 v[120:121], v[120:121], 0, s[68:69]
	v_cvt_pk_bf16_f32 v114, v122, v123
	v_cvt_pk_bf16_f32 v115, v124, v125
	v_lshl_add_u64 v[120:121], v[120:121], 0, v[96:97]
	global_store_dwordx4 v[120:121], v[114:117], off sc1
	s_nop 1
	v_or_b32_e32 v114, 16, v130
	v_ashrrev_i32_e32 v115, 31, v114
	v_lshlrev_b64 v[116:117], 6, v[114:115]
	v_lshl_add_u64 v[116:117], v[204:205], 0, v[116:117]
	s_waitcnt vmcnt(7)
	v_add_f32_e32 v115, v140, v141
	v_add_f32_e32 v116, v142, v143
	v_add_f32_e32 v115, v115, v116
	v_mov_b32_e32 v116, v115
	s_nop 1
	v_permlane16_swap_b32_e32 v115, v116
	v_add_f32_e32 v115, v115, v116
	v_mov_b32_e32 v116, v115
	s_nop 1
	v_permlane32_swap_b32_e32 v115, v116
	v_add_f32_e32 v115, v115, v116
	v_fmamk_f32 v115, v115, 0x3a800000, v225
	v_cmp_gt_f32_e32 vcc, s3, v115
	v_mul_f32_e32 v116, 0x4b800000, v115
	s_nop 0
	v_cndmask_b32_e32 v115, v115, v116, vcc
	v_rsq_f32_e32 v115, v115
	s_nop 0
	v_mul_f32_e32 v116, 0x45800000, v115
	v_cndmask_b32_e32 v116, v115, v116, vcc
	v_pk_mul_f32 v[110:111], v[110:111], v[116:117] op_sel_hi:[1,0]
	v_pk_mul_f32 v[106:107], v[106:107], v[116:117] op_sel_hi:[1,0]
	v_mul_f32_e32 v115, 0xbfb8aa3b, v110
	v_exp_f32_e32 v115, v115
	v_pk_mul_f32 v[108:109], v[108:109], v[116:117] op_sel_hi:[1,0]
	v_pk_mul_f32 v[102:103], v[102:103], v[116:117] op_sel_hi:[1,0]
	v_pk_mul_f32 v[98:99], v[98:99], v[116:117] op_sel_hi:[1,0]
	v_add_f32_e32 v115, 1.0, v115
	v_rcp_f32_e32 v120, v115
	v_mul_f32_e32 v115, 0xbfb8aa3b, v111
	v_exp_f32_e32 v115, v115
	v_pk_mul_f32 v[100:101], v[100:101], v[116:117] op_sel_hi:[1,0]
	v_add_f32_e32 v115, 1.0, v115
	v_rcp_f32_e32 v121, v115
	s_nop 0
	v_pk_mul_f32 v[110:111], v[110:111], v[120:121]
	s_nop 0
	v_pk_mul_f32 v[106:107], v[106:107], v[110:111]
	v_pk_mul_f32 v[110:111], v[112:113], v[116:117] op_sel_hi:[1,0]
	s_nop 0
	v_mul_f32_e32 v112, 0xbfb8aa3b, v110
	v_mul_f32_e32 v113, 0xbfb8aa3b, v111
	v_exp_f32_e32 v112, v112
	v_exp_f32_e32 v113, v113
	v_add_f32_e32 v112, 1.0, v112
	v_add_f32_e32 v113, 1.0, v113
	v_rcp_f32_e32 v112, v112
	v_rcp_f32_e32 v113, v113
	s_nop 0
	v_pk_mul_f32 v[110:111], v[110:111], v[112:113]
	s_nop 0
	v_pk_mul_f32 v[108:109], v[108:109], v[110:111]
	v_mul_f32_e32 v110, 0xbfb8aa3b, v102
	v_mul_f32_e32 v111, 0xbfb8aa3b, v103
	v_exp_f32_e32 v110, v110
	v_exp_f32_e32 v111, v111
	v_add_f32_e32 v110, 1.0, v110
	v_add_f32_e32 v111, 1.0, v111
	v_rcp_f32_e32 v110, v110
	v_rcp_f32_e32 v111, v111
	s_nop 0
	v_pk_mul_f32 v[102:103], v[102:103], v[110:111]
	s_nop 0
	v_pk_mul_f32 v[102:103], v[98:99], v[102:103]
	v_pk_mul_f32 v[98:99], v[104:105], v[116:117] op_sel_hi:[1,0]
	s_nop 0
	v_mul_f32_e32 v104, 0xbfb8aa3b, v98
	v_mul_f32_e32 v105, 0xbfb8aa3b, v99
	v_exp_f32_e32 v104, v104
	v_exp_f32_e32 v105, v105
	v_add_f32_e32 v104, 1.0, v104
	v_add_f32_e32 v105, 1.0, v105
	v_rcp_f32_e32 v104, v104
	v_rcp_f32_e32 v105, v105
	s_nop 0
	v_pk_mul_f32 v[98:99], v[98:99], v[104:105]
	s_nop 0
	v_pk_mul_f32 v[104:105], v[100:101], v[98:99]
	v_cvt_pk_bf16_f32 v100, v102, v103
	v_mad_i64_i32 v[102:103], s[4:5], v114, s16, v[118:119]
	v_lshl_add_u64 v[102:103], v[102:103], 0, s[38:39]
	v_lshl_add_u64 v[102:103], v[102:103], 0, s[68:69]
	v_cvt_pk_bf16_f32 v98, v106, v107
	v_cvt_pk_bf16_f32 v99, v108, v109
	v_cvt_pk_bf16_f32 v101, v104, v105
	v_lshl_add_u64 v[102:103], v[102:103], 0, v[96:97]
	global_store_dwordx4 v[102:103], v[98:101], off sc1
	s_nop 1
	v_or_b32_e32 v98, 32, v130
	v_ashrrev_i32_e32 v99, 31, v98
	v_lshlrev_b64 v[100:101], 6, v[98:99]
	v_lshl_add_u64 v[100:101], v[204:205], 0, v[100:101]
	s_waitcnt vmcnt(7)
	v_add_f32_e32 v99, v144, v145
	v_add_f32_e32 v100, v146, v147
	v_add_f32_e32 v99, v99, v100
	v_mov_b32_e32 v100, v99
	s_nop 1
	v_permlane16_swap_b32_e32 v99, v100
	v_add_f32_e32 v99, v99, v100
	v_mov_b32_e32 v100, v99
	s_nop 1
	v_permlane32_swap_b32_e32 v99, v100
	v_add_f32_e32 v99, v99, v100
	v_fmamk_f32 v99, v99, 0x3a800000, v225
	v_cmp_gt_f32_e32 vcc, s3, v99
	v_mul_f32_e32 v100, 0x4b800000, v99
	s_nop 0
	v_cndmask_b32_e32 v99, v99, v100, vcc
	v_rsq_f32_e32 v99, v99
	s_nop 0
	v_mul_f32_e32 v100, 0x45800000, v99
	v_cndmask_b32_e32 v100, v99, v100, vcc
	v_pk_mul_f32 v[92:93], v[92:93], v[100:101] op_sel_hi:[1,0]
	v_pk_mul_f32 v[88:89], v[88:89], v[100:101] op_sel_hi:[1,0]
	v_mul_f32_e32 v99, 0xbfb8aa3b, v92
	v_exp_f32_e32 v99, v99
	v_pk_mul_f32 v[90:91], v[90:91], v[100:101] op_sel_hi:[1,0]
	v_pk_mul_f32 v[84:85], v[84:85], v[100:101] op_sel_hi:[1,0]
	v_pk_mul_f32 v[80:81], v[80:81], v[100:101] op_sel_hi:[1,0]
	v_add_f32_e32 v99, 1.0, v99
	v_rcp_f32_e32 v102, v99
	v_mul_f32_e32 v99, 0xbfb8aa3b, v93
	v_exp_f32_e32 v99, v99
	v_pk_mul_f32 v[82:83], v[82:83], v[100:101] op_sel_hi:[1,0]
	v_add_f32_e32 v99, 1.0, v99
	v_rcp_f32_e32 v103, v99
	s_nop 0
	v_pk_mul_f32 v[92:93], v[92:93], v[102:103]
	s_nop 0
	v_pk_mul_f32 v[88:89], v[88:89], v[92:93]
	v_pk_mul_f32 v[92:93], v[94:95], v[100:101] op_sel_hi:[1,0]
	s_nop 0
	v_mul_f32_e32 v94, 0xbfb8aa3b, v92
	v_mul_f32_e32 v95, 0xbfb8aa3b, v93
	v_exp_f32_e32 v94, v94
	v_exp_f32_e32 v95, v95
	v_add_f32_e32 v94, 1.0, v94
	v_add_f32_e32 v95, 1.0, v95
	v_rcp_f32_e32 v94, v94
	v_rcp_f32_e32 v95, v95
	s_nop 0
	v_pk_mul_f32 v[92:93], v[92:93], v[94:95]
	s_nop 0
	v_pk_mul_f32 v[90:91], v[90:91], v[92:93]
	v_mul_f32_e32 v92, 0xbfb8aa3b, v84
	v_mul_f32_e32 v93, 0xbfb8aa3b, v85
	v_exp_f32_e32 v92, v92
	v_exp_f32_e32 v93, v93
	v_add_f32_e32 v92, 1.0, v92
	v_add_f32_e32 v93, 1.0, v93
	v_rcp_f32_e32 v92, v92
	v_rcp_f32_e32 v93, v93
	s_nop 0
	v_pk_mul_f32 v[84:85], v[84:85], v[92:93]
	s_nop 0
	v_pk_mul_f32 v[84:85], v[80:81], v[84:85]
	v_pk_mul_f32 v[80:81], v[86:87], v[100:101] op_sel_hi:[1,0]
	s_nop 0
	v_mul_f32_e32 v86, 0xbfb8aa3b, v80
	v_mul_f32_e32 v87, 0xbfb8aa3b, v81
	v_exp_f32_e32 v86, v86
	v_exp_f32_e32 v87, v87
	v_add_f32_e32 v86, 1.0, v86
	v_add_f32_e32 v87, 1.0, v87
	v_rcp_f32_e32 v86, v86
	v_rcp_f32_e32 v87, v87
	s_nop 0
	v_pk_mul_f32 v[80:81], v[80:81], v[86:87]
	s_nop 0
	v_pk_mul_f32 v[86:87], v[82:83], v[80:81]
	v_cvt_pk_bf16_f32 v82, v84, v85
	v_mad_i64_i32 v[84:85], s[4:5], v98, s16, v[118:119]
	v_lshl_add_u64 v[84:85], v[84:85], 0, s[38:39]
	v_lshl_add_u64 v[84:85], v[84:85], 0, s[68:69]
	v_cvt_pk_bf16_f32 v80, v88, v89
	v_cvt_pk_bf16_f32 v81, v90, v91
	v_cvt_pk_bf16_f32 v83, v86, v87
	v_lshl_add_u64 v[84:85], v[84:85], 0, v[96:97]
	global_store_dwordx4 v[84:85], v[80:83], off sc1
	s_nop 1
	v_or_b32_e32 v80, 48, v130
	v_ashrrev_i32_e32 v81, 31, v80
	v_lshlrev_b64 v[82:83], 6, v[80:81]
	v_lshl_add_u64 v[82:83], v[204:205], 0, v[82:83]
	s_waitcnt vmcnt(7)
	v_add_f32_e32 v81, v148, v149
	v_add_f32_e32 v82, v150, v151
	v_add_f32_e32 v81, v81, v82
	v_mov_b32_e32 v82, v81
	s_nop 1
	v_permlane16_swap_b32_e32 v81, v82
	v_add_f32_e32 v81, v81, v82
	v_mov_b32_e32 v82, v81
	s_nop 1
	v_permlane32_swap_b32_e32 v81, v82
	v_add_f32_e32 v81, v81, v82
	v_fmamk_f32 v81, v81, 0x3a800000, v225
	v_cmp_gt_f32_e32 vcc, s3, v81
	v_mul_f32_e32 v82, 0x4b800000, v81
	s_nop 0
	v_cndmask_b32_e32 v81, v81, v82, vcc
	v_rsq_f32_e32 v81, v81
	s_nop 0
	v_mul_f32_e32 v82, 0x45800000, v81
	v_cndmask_b32_e32 v82, v81, v82, vcc
	v_pk_mul_f32 v[76:77], v[76:77], v[82:83] op_sel_hi:[1,0]
	v_pk_mul_f32 v[72:73], v[72:73], v[82:83] op_sel_hi:[1,0]
	v_mul_f32_e32 v81, 0xbfb8aa3b, v76
	v_exp_f32_e32 v81, v81
	v_pk_mul_f32 v[74:75], v[74:75], v[82:83] op_sel_hi:[1,0]
	v_pk_mul_f32 v[68:69], v[68:69], v[82:83] op_sel_hi:[1,0]
	v_pk_mul_f32 v[64:65], v[64:65], v[82:83] op_sel_hi:[1,0]
	v_add_f32_e32 v81, 1.0, v81
	v_rcp_f32_e32 v84, v81
	v_mul_f32_e32 v81, 0xbfb8aa3b, v77
	v_exp_f32_e32 v81, v81
	v_pk_mul_f32 v[66:67], v[66:67], v[82:83] op_sel_hi:[1,0]
	v_cmp_ne_u32_e32 vcc, 0, v247
	s_and_b64 vcc, exec, vcc
	v_add_f32_e32 v81, 1.0, v81
	v_rcp_f32_e32 v85, v81
	s_nop 0
	v_pk_mul_f32 v[76:77], v[76:77], v[84:85]
	s_nop 0
	v_pk_mul_f32 v[72:73], v[72:73], v[76:77]
	v_pk_mul_f32 v[76:77], v[78:79], v[82:83] op_sel_hi:[1,0]
	s_nop 0
	v_mul_f32_e32 v78, 0xbfb8aa3b, v76
	v_mul_f32_e32 v79, 0xbfb8aa3b, v77
	v_exp_f32_e32 v78, v78
	v_exp_f32_e32 v79, v79
	v_add_f32_e32 v78, 1.0, v78
	v_add_f32_e32 v79, 1.0, v79
	v_rcp_f32_e32 v78, v78
	v_rcp_f32_e32 v79, v79
	s_nop 0
	v_pk_mul_f32 v[76:77], v[76:77], v[78:79]
	s_nop 0
	v_pk_mul_f32 v[74:75], v[74:75], v[76:77]
	v_mul_f32_e32 v76, 0xbfb8aa3b, v68
	v_mul_f32_e32 v77, 0xbfb8aa3b, v69
	v_exp_f32_e32 v76, v76
	v_exp_f32_e32 v77, v77
	v_add_f32_e32 v76, 1.0, v76
	v_add_f32_e32 v77, 1.0, v77
	v_rcp_f32_e32 v76, v76
	v_rcp_f32_e32 v77, v77
	s_nop 0
	v_pk_mul_f32 v[68:69], v[68:69], v[76:77]
	s_nop 0
	v_pk_mul_f32 v[68:69], v[64:65], v[68:69]
	v_pk_mul_f32 v[64:65], v[70:71], v[82:83] op_sel_hi:[1,0]
	s_nop 0
	v_mul_f32_e32 v70, 0xbfb8aa3b, v64
	v_mul_f32_e32 v71, 0xbfb8aa3b, v65
	v_exp_f32_e32 v70, v70
	v_exp_f32_e32 v71, v71
	v_add_f32_e32 v70, 1.0, v70
	v_add_f32_e32 v71, 1.0, v71
	v_rcp_f32_e32 v70, v70
	v_rcp_f32_e32 v71, v71
	s_nop 0
	v_pk_mul_f32 v[64:65], v[64:65], v[70:71]
	s_nop 0
	v_pk_mul_f32 v[70:71], v[66:67], v[64:65]
	v_cvt_pk_bf16_f32 v66, v68, v69
	v_mad_i64_i32 v[68:69], s[4:5], v80, s16, v[118:119]
	v_lshl_add_u64 v[68:69], v[68:69], 0, s[38:39]
	v_lshl_add_u64 v[68:69], v[68:69], 0, s[68:69]
	v_cvt_pk_bf16_f32 v64, v72, v73
	v_cvt_pk_bf16_f32 v65, v74, v75
	v_cvt_pk_bf16_f32 v67, v70, v71
	v_lshl_add_u64 v[68:69], v[68:69], 0, v[96:97]
	global_store_dwordx4 v[68:69], v[64:67], off sc1
	s_cbranch_vccz .LBB0_382
	s_waitcnt vmcnt(4)
	s_and_b64 vcc, exec, s[36:37]
	s_mov_b64 s[30:31], -1
	s_cbranch_vccnz .LBB0_349
	s_branch .LBB0_383

.LBB0_540:
	v_lshl_add_u32 v130, s68, 8, v205
	v_ashrrev_i32_e32 v131, 31, v130
	v_lshlrev_b64 v[132:133], 6, v[130:131]
	v_lshl_add_u64 v[132:133], v[206:207], 0, v[132:133]
	global_load_dwordx4 v[146:149], v[132:133], off
	global_load_dwordx4 v[150:153], v[132:133], off offset:1024
	global_load_dwordx4 v[154:157], v[132:133], off offset:2048
	global_load_dwordx4 v[158:161], v[132:133], off offset:3072
	v_add_u32_e32 v178, 0x80, v130
	v_ashrrev_i32_e32 v179, 31, v178
	v_lshlrev_b64 v[178:179], 6, v[178:179]
	v_lshl_add_u64 v[178:179], v[206:207], 0, v[178:179]
	global_load_dwordx4 v[162:165], v[178:179], off
	global_load_dwordx4 v[166:169], v[178:179], off offset:1024
	global_load_dwordx4 v[170:173], v[178:179], off offset:2048
	global_load_dwordx4 v[174:177], v[178:179], off offset:3072
	s_and_b64 vcc, exec, s[54:55]
	s_cbranch_vccz .LBB0_542
	s_barrier
.LBB0_542:
	s_cmp_gt_i32 s77, 7
	s_cselect_b64 s[40:41], -1, 0
	s_lshl_b32 s30, s77, 8
	s_add_i32 s68, s30, 0xfffff800
	s_mov_b64 s[38:39], -1
	s_waitcnt vmcnt(7)
	v_add_f32_e32 v96, v146, v147
	v_add_f32_e32 v132, v148, v149
	v_add_f32_e32 v96, v96, v132
	v_mov_b32_e32 v132, v96
	s_nop 1
	v_permlane16_swap_b32_e32 v96, v132
	v_add_f32_e32 v96, v96, v132
	v_mov_b32_e32 v132, v96
	s_nop 1
	v_permlane32_swap_b32_e32 v96, v132
	v_add_f32_e32 v96, v96, v132
	v_fmamk_f32 v96, v96, 0x3a800000, v225
	v_cmp_gt_f32_e32 vcc, s3, v96
	v_mul_f32_e32 v132, 0x4b800000, v96
	v_lshlrev_b64 v[134:135], 11, v[130:131]
	v_cndmask_b32_e32 v96, v96, v132, vcc
	v_rsq_f32_e32 v96, v96
	s_nop 0
	v_mul_f32_e32 v132, 0x45800000, v96
	v_cndmask_b32_e32 v132, v96, v132, vcc
	s_and_b64 vcc, exec, s[40:41]
	v_lshlrev_b32_e32 v96, 1, v204
	s_cbranch_vccz .LBB0_544
	v_lshl_add_u64 v[136:137], s[26:27], 0, v[134:135]
	v_lshl_add_u64 v[136:137], s[68:69], 1, v[136:137]
	s_lshl_b32 s30, s62, 1
	s_mov_b32 s31, s69
	v_lshl_add_u64 v[136:137], v[136:137], 0, s[30:31]
	v_lshl_add_u64 v[140:141], v[136:137], 0, v[96:97]
	v_pk_mul_f32 v[138:139], v[128:129], v[132:133] op_sel_hi:[1,0]
	v_pk_mul_f32 v[136:137], v[126:127], v[132:133] op_sel_hi:[1,0]
	v_pk_mul_f32 v[142:143], v[120:121], v[132:133] op_sel_hi:[1,0]
	v_pk_mul_f32 v[144:145], v[118:119], v[132:133] op_sel_hi:[1,0]
	v_cvt_pk_bf16_f32 v136, v136, v137
	v_cvt_pk_bf16_f32 v137, v138, v139
	v_cvt_pk_bf16_f32 v138, v144, v145
	v_cvt_pk_bf16_f32 v139, v142, v143
	global_store_dwordx4 v[140:141], v[136:139], off sc1
	v_pk_mul_f32 v[142:143], v[116:117], v[132:133] op_sel_hi:[1,0]
	v_pk_mul_f32 v[144:145], v[114:115], v[132:133] op_sel_hi:[1,0]
	v_pk_mul_f32 v[138:139], v[124:125], v[132:133] op_sel_hi:[1,0]
	v_pk_mul_f32 v[136:137], v[122:123], v[132:133] op_sel_hi:[1,0]
	s_mov_b64 s[38:39], 0
	v_cvt_pk_bf16_f32 v136, v136, v137
	v_cvt_pk_bf16_f32 v137, v138, v139
	v_cvt_pk_bf16_f32 v138, v144, v145
	v_cvt_pk_bf16_f32 v139, v142, v143
	global_store_dwordx4 v[140:141], v[136:139], off offset:256 sc1
